# all layer 1-3 weight transposes (except memory KV weights) deferred to the scan CU-mates, 150 tiles per mate
# speedup vs baseline: 1.1226x; 1.0063x over previous
; __device__ __forceinline__ void phase_w(const Params p, char* smem) {
;     ...
;   for (int t = lbid(); t < L_ * PER_L; t += gridDim.x) {
;     int l = t / PER_L, r = t % PER_L;
;     if (r < 7392) {
;       transpose_tile<true>((const float*)p.in[I_WIN] + (size_t)l * D_ * NIN, NIN, (u16*)(ws + OFF_WIN) + (size_t)l * NINP * D_, D_,
;                      r / 231, r % 231, tile);
.LBB0_149:
	s_lshr_b32 s0, s73, 6
	s_cmp_eq_u32 s0, 4
	s_cbranch_scc0 .Lnot_mate
	v_readlane_b32 s0, v244, 43
	s_cmp_gt_u32 s0, 2
	s_cbranch_scc1 .LBB0_248
	s_add_i32 s0, s0, 1
	s_mul_i32 s20, s0, 0x2768
	s_add_i32 s101, s20, 0x2567
	s_add_i32 s20, s20, s73
	s_sub_i32 s20, s20, 0x100
	s_mov_b32 s100, 64
	s_branch .Ltramp_554
.Lnot_mate:
	s_cmp_lt_u32 s73, 64
	s_cbranch_scc1 .Ltail_skip
	s_sub_i32 s24, s73, 64
	s_cmp_lt_u32 s73, 256
	s_cbranch_scc1 .Ltail_go
	s_cmp_lt_u32 s73, 320
	s_cbranch_scc1 .Ltail_skip
	s_cmp_gt_u32 s73, 383
	s_cbranch_scc1 .Ltail_skip
	s_sub_i32 s24, s73, 128

; __device__ __forceinline__ void phase_w(const Params p, char* smem) {
;     ...
;   for (int t = lbid(); t < L_ * PER_L; t += gridDim.x) {
;     int l = t / PER_L, r = t % PER_L;
.LBB0_552:
	s_mov_b32 s20, s73
	s_movk_i32 s100, 0x200
	s_movk_i32 s101, 0x2767
	s_branch .LBB0_554
.LBB0_553:
	s_waitcnt vmcnt(5) lgkmcnt(0)
	v_cvt_pk_bf16_f32 v4, v4, v5
	v_cvt_pk_bf16_f32 v3, v2, v3
	v_cvt_pk_bf16_f32 v2, v0, v1
	global_store_dwordx3 v[6:7], v[2:4], off offset:4
	s_add_i32 s20, s20, s100
; __device__ __forceinline__ void phase_w(const Params p, char* smem) {
;     ...
;   for (int t = lbid(); t < L_ * PER_L; t += gridDim.x) {
;     int l = t / PER_L, r = t % PER_L;
;     if (r < 7392) {
;       transpose_tile<true>((const float*)p.in[I_WIN] + (size_t)l * D_ * NIN, NIN, (u16*)(ws + OFF_WIN) + (size_t)l * NINP * D_, D_,
;                      r / 231, r % 231, tile);
;     } else if (r < 7392 + 1024) {
;       r -= 7392;
;       int bi = r >> 8;
;       r &= 255;
;       transpose_tile<false>((const float*)p.in[I_WBR] + (size_t)(l * 4 + bi) * 512 * 2048, 2048,
;                      (u16*)(ws + OFF_WB) + (size_t)(l * 4 + bi) * 2048 * 512, 512, r >> 5, r & 31, tile);
;     } else if (r < 7392 + 2048) {
;       r -= 7392 + 1024;
;       transpose_tile<false>((const float*)p.in[I_WOUT] + (size_t)l * 2048 * 2048, 2048, (u16*)(ws + OFF_WO) + (size_t)l * 2048 * 2048,
;                      2048, r >> 5, r & 31, tile);
;     } else if (r < 7392 + 2048 + 72) {
;       r -= 7392 + 2048;
;       transpose_tile<false>((const float*)p.in[I_WUQ] + (size_t)l * 384 * 768, 768, (u16*)(ws + OFF_WUQ) + (size_t)l * 768 * 384, 384,
;                      r / 12, r % 12, tile);
;     } else if (r < 7392 + 2048 + 72 + 64) {
;       r -= 7392 + 2048 + 72;
;       transpose_tile<false>((const float*)p.in[I_WUKV] + (size_t)l * 256 * 1024, 1024, (u16*)(ws + OFF_WUKV) + (size_t)l * 1024 * 256,
;                      256, r >> 4, r & 15, tile);
;     } else {
;       r -= 7392 + 2048 + 72 + 64;
;       transpose_tile<false>((const float*)p.in[I_WKV] + (size_t)l * 2048 * 1024, 1024, (u16*)(ws + OFF_WKV) + (size_t)l * 1024 * 2048,
;                      2048, r >> 4, r & 15, tile);
;     }
;   }
.LBB0_554:
	s_cmp_gt_i32 s20, s101
	s_cbranch_scc1 .Lw_exit
	s_mul_hi_i32 s0, s20, 0x67f1620f
	s_lshr_b32 s1, s0, 31
	s_ashr_i32 s0, s0, 12
	s_add_i32 s0, s0, s1
	s_mul_i32 s1, s0, 0x2768
	s_sub_i32 s21, s20, s1
	s_cmpk_gt_i32 s21, 0x1cdf
	s_mov_b64 s[2:3], -1
	s_cbranch_scc0 .LBB0_573
	s_cmpk_gt_u32 s21, 0x20df
	s_cbranch_scc0 .LBB0_570
	s_cmpk_gt_u32 s21, 0x24df
	s_cbranch_scc0 .LBB0_567
	s_cmpk_gt_u32 s21, 0x2527
	s_cbranch_scc0 .LBB0_564
	s_ashr_i32 s1, s0, 31
	s_cmpk_gt_u32 s21, 0x2567
	s_cbranch_scc0 .LBB0_561
	v_readlane_b32 s36, v247, 12
	s_add_i32 s22, s21, 0xffffda98
	s_lshl_b64 s[2:3], s[0:1], 23
	v_readlane_b32 s50, v247, 26
	v_readlane_b32 s51, v247, 27
	s_add_u32 s23, s50, s2
	s_addc_u32 s24, s51, s3
	s_lshl_b64 s[2:3], s[0:1], 22
	v_readlane_b32 s25, v246, 21
	s_add_u32 s25, s25, s2
	v_readlane_b32 s2, v246, 22
	s_addc_u32 s3, s2, s3
	s_lshl_b32 s2, s22, 2
	s_waitcnt vmcnt(1)
	v_mov_b32_e32 v20, v171
	s_and_b32 s30, s2, 0x7fffffc0
	s_lshl_b32 s2, s22, 6
	s_and_b32 s2, s2, 0x3c0
	v_ashrrev_i32_e32 v21, 6, v20
	s_lshl_b32 s22, s2, 2
	v_add_u32_e32 v2, s30, v21
	s_add_u32 s22, s23, s22
	v_lshlrev_b32_e32 v0, 2, v20
	v_add_u32_e32 v6, 4, v2
	v_add_u32_e32 v8, 8, v2
	v_add_u32_e32 v18, 28, v2
	s_addc_u32 s23, s24, 0
	v_and_b32_e32 v168, 0xfc, v0
	v_ashrrev_i32_e32 v3, 31, v2
	s_waitcnt lgkmcnt(0)
	v_ashrrev_i32_e32 v7, 31, v6
	v_ashrrev_i32_e32 v9, 31, v8
	v_add_u32_e32 v10, 12, v2
	v_add_u32_e32 v12, 16, v2
	v_add_u32_e32 v14, 20, v2
	v_add_u32_e32 v16, 24, v2
	v_ashrrev_i32_e32 v19, 31, v18
	v_lshl_add_u64 v[0:1], s[22:23], 0, v[168:169]
	v_lshlrev_b64 v[4:5], 12, v[2:3]
	v_lshlrev_b64 v[6:7], 12, v[6:7]
	v_lshlrev_b64 v[8:9], 12, v[8:9]
	v_ashrrev_i32_e32 v11, 31, v10
	v_ashrrev_i32_e32 v13, 31, v12
	v_ashrrev_i32_e32 v15, 31, v14
	v_ashrrev_i32_e32 v17, 31, v16
	v_lshlrev_b64 v[18:19], 12, v[18:19]
	v_lshl_add_u64 v[4:5], v[0:1], 0, v[4:5]
	v_lshl_add_u64 v[6:7], v[0:1], 0, v[6:7]
	v_lshl_add_u64 v[8:9], v[0:1], 0, v[8:9]
	v_lshlrev_b64 v[10:11], 12, v[10:11]
	v_lshlrev_b64 v[12:13], 12, v[12:13]
	v_lshlrev_b64 v[14:15], 12, v[14:15]
	v_lshlrev_b64 v[16:17], 12, v[16:17]
	v_lshl_add_u64 v[18:19], v[0:1], 0, v[18:19]
	s_barrier
	v_lshl_add_u64 v[10:11], v[0:1], 0, v[10:11]
	v_lshl_add_u64 v[12:13], v[0:1], 0, v[12:13]
	v_lshl_add_u64 v[14:15], v[0:1], 0, v[14:15]
	v_lshl_add_u64 v[16:17], v[0:1], 0, v[16:17]
	global_load_dword v22, v[4:5], off
	global_load_dword v23, v[6:7], off
	global_load_dword v24, v[8:9], off
	global_load_dword v25, v[10:11], off
	global_load_dword v26, v[12:13], off
	global_load_dword v27, v[14:15], off
	global_load_dword v28, v[16:17], off
	s_nop 0
	global_load_dword v18, v[18:19], off
	v_add_u32_e32 v4, 32, v2
	v_add_u32_e32 v6, 36, v2
	v_add_u32_e32 v8, 40, v2
	v_ashrrev_i32_e32 v5, 31, v4
	v_ashrrev_i32_e32 v7, 31, v6
	v_ashrrev_i32_e32 v9, 31, v8
	v_add_u32_e32 v10, 44, v2
	v_add_u32_e32 v12, 48, v2
	v_add_u32_e32 v14, 52, v2
	v_add_u32_e32 v16, 56, v2
	v_add_u32_e32 v2, 60, v2
	v_lshlrev_b64 v[4:5], 12, v[4:5]
	v_lshlrev_b64 v[6:7], 12, v[6:7]
	v_lshlrev_b64 v[8:9], 12, v[8:9]
	v_ashrrev_i32_e32 v11, 31, v10
	v_ashrrev_i32_e32 v13, 31, v12
	v_ashrrev_i32_e32 v15, 31, v14
	v_ashrrev_i32_e32 v17, 31, v16
	v_ashrrev_i32_e32 v3, 31, v2
	v_lshl_add_u64 v[4:5], v[0:1], 0, v[4:5]
	v_lshl_add_u64 v[6:7], v[0:1], 0, v[6:7]
	v_lshl_add_u64 v[8:9], v[0:1], 0, v[8:9]
	v_lshlrev_b64 v[10:11], 12, v[10:11]
	v_lshlrev_b64 v[12:13], 12, v[12:13]
	v_lshlrev_b64 v[14:15], 12, v[14:15]
	v_lshlrev_b64 v[16:17], 12, v[16:17]
	v_lshlrev_b64 v[2:3], 12, v[2:3]
	v_lshl_add_u64 v[10:11], v[0:1], 0, v[10:11]
	v_lshl_add_u64 v[12:13], v[0:1], 0, v[12:13]
	v_lshl_add_u64 v[14:15], v[0:1], 0, v[14:15]
	v_lshl_add_u64 v[16:17], v[0:1], 0, v[16:17]
	v_lshl_add_u64 v[0:1], v[0:1], 0, v[2:3]
	global_load_dword v2, v[4:5], off
	global_load_dword v3, v[6:7], off
	s_nop 0
	global_load_dword v4, v[8:9], off
	global_load_dword v5, v[10:11], off
	global_load_dword v6, v[12:13], off
	global_load_dword v7, v[14:15], off
	s_nop 0
	global_load_dword v8, v[16:17], off
	global_load_dword v9, v[0:1], off
	s_movk_i32 s24, 0x104
	v_mad_u64_u32 v[0:1], s[22:23], v21, s24, v[168:169]
	s_waitcnt vmcnt(15)
	ds_write_b32 v0, v22
	s_waitcnt vmcnt(14)
	ds_write_b32 v0, v23 offset:1040
	s_waitcnt vmcnt(13)
	ds_write_b32 v0, v24 offset:2080
	s_waitcnt vmcnt(12)
	ds_write_b32 v0, v25 offset:3120
	s_waitcnt vmcnt(11)
	ds_write_b32 v0, v26 offset:4160
	s_waitcnt vmcnt(10)
	ds_write_b32 v0, v27 offset:5200
	s_waitcnt vmcnt(9)
	ds_write_b32 v0, v28 offset:6240
	s_waitcnt vmcnt(8)
	ds_write_b32 v0, v18 offset:7280
	s_waitcnt vmcnt(7)
	ds_write_b32 v0, v2 offset:8320
	s_waitcnt vmcnt(6)
	ds_write_b32 v0, v3 offset:9360
	s_waitcnt vmcnt(5)
	ds_write_b32 v0, v4 offset:10400
	s_waitcnt vmcnt(4)
	ds_write_b32 v0, v5 offset:11440
	s_waitcnt vmcnt(3)
	ds_write_b32 v0, v6 offset:12480
	s_waitcnt vmcnt(2)
	ds_write_b32 v0, v7 offset:13520
	s_waitcnt vmcnt(1)
	ds_write_b32 v0, v8 offset:14560
	s_waitcnt vmcnt(0)
	ds_write_b32 v0, v9 offset:15600
	v_lshlrev_b32_e32 v0, 3, v20
	v_ashrrev_i32_e32 v11, 3, v20
	v_and_b32_e32 v10, 56, v0
	v_lshlrev_b32_e32 v0, 2, v11
	v_mad_u32_u24 v4, v10, s24, v0
	s_waitcnt lgkmcnt(0)
	s_barrier
	ds_read2_b32 v[0:1], v4 offset1:65
	ds_read2_b32 v[2:3], v4 offset0:130 offset1:195
	v_add_u32_e32 v6, 0x400, v4
	ds_read2_b32 v[4:5], v6 offset0:4 offset1:69
	ds_read2_b32 v[6:7], v6 offset0:134 offset1:199
	s_lshl_b32 s22, s30, 1
	s_waitcnt lgkmcnt(3)
	v_cvt_pk_bf16_f32 v0, v0, v1
	s_waitcnt lgkmcnt(2)
	v_cvt_pk_bf16_f32 v1, v2, v3
	s_waitcnt lgkmcnt(1)
	v_cvt_pk_bf16_f32 v2, v4, v5
	v_add_u32_e32 v5, 0x100, v20
	v_add_u32_e32 v4, s2, v11
	v_ashrrev_i32_e32 v11, 3, v5
	v_lshlrev_b32_e32 v5, 2, v11
	s_add_u32 s22, s25, s22
	v_lshlrev_b32_e32 v168, 1, v10
	v_mad_u32_u24 v10, v10, s24, v5
	s_addc_u32 s23, s3, 0
	s_waitcnt lgkmcnt(0)
	v_cvt_pk_bf16_f32 v3, v6, v7
	ds_read2_b32 v[6:7], v10 offset1:65
	v_ashrrev_i32_e32 v5, 31, v4
	v_lshl_add_u64 v[8:9], s[22:23], 0, v[168:169]
	v_lshlrev_b64 v[4:5], 12, v[4:5]
	v_lshl_add_u64 v[4:5], v[8:9], 0, v[4:5]
	global_store_dwordx4 v[4:5], v[0:3], off
	v_add_u32_e32 v4, 0x400, v10
	ds_read2_b32 v[0:1], v10 offset0:130 offset1:195
	ds_read2_b32 v[2:3], v4 offset0:4 offset1:69
	ds_read2_b32 v[4:5], v4 offset0:134 offset1:199
	s_waitcnt lgkmcnt(3)
	v_cvt_pk_bf16_f32 v12, v6, v7
	v_add_u32_e32 v6, s2, v11
	v_ashrrev_i32_e32 v7, 31, v6
	v_lshlrev_b64 v[6:7], 12, v[6:7]
	v_readlane_b32 s48, v247, 24
	v_lshl_add_u64 v[6:7], v[8:9], 0, v[6:7]
	v_readlane_b32 s37, v247, 13
	v_readlane_b32 s38, v247, 14
	v_readlane_b32 s39, v247, 15
	v_readlane_b32 s40, v247, 16
	v_readlane_b32 s41, v247, 17
	v_readlane_b32 s42, v247, 18
	v_readlane_b32 s43, v247, 19
	v_readlane_b32 s44, v247, 20
	v_readlane_b32 s45, v247, 21
	v_readlane_b32 s46, v247, 22
	v_readlane_b32 s47, v247, 23
	v_readlane_b32 s49, v247, 25
	v_readlane_b32 s48, v244, 34
	v_readlane_b32 s50, v244, 33
	s_movk_i32 s51, 0x3ff
	global_store_dword v[6:7], v12, off
	s_mov_b64 s[2:3], 0

; __device__ __forceinline__ void phase_w(const Params p, char* smem) {
;     ...
;   for (int t = lbid(); t < L_ * PER_L; t += gridDim.x) {
;     int l = t / PER_L, r = t % PER_L;
.Lw_exit:
	s_cmp_eq_u32 s100, 64
	s_cbranch_scc1 .Lw_ret4
	s_cmp_eq_u32 s101, 0x9d9f
	s_cbranch_scc1 .LBB0_575
	s_add_i32 s101, s101, 0x2768
	s_sub_i32 s20, s101, 0x1ff
	s_add_i32 s20, s20, s73
	s_branch .LBB0_554
.Lw_ret4:
	v_readlane_b32 s50, v244, 33
	s_movk_i32 s51, 0x3ff
	v_readlane_b32 s48, v244, 34
	s_branch .Ltramp_248

; __global__ void __launch_bounds__(256, 2) mega(Params p, int ph_lo, int ph_hi) {
;   __shared__ __attribute__((aligned(16))) char smem[SMEM_BYTES];
	.amdhsa_kernel _Z4mega6Paramsii
		.amdhsa_group_segment_fixed_size 49180
		.amdhsa_private_segment_fixed_size 0
		.amdhsa_kernarg_size 520
		.amdhsa_user_sgpr_count 2
		.amdhsa_user_sgpr_dispatch_ptr 0
		.amdhsa_user_sgpr_queue_ptr 0
		.amdhsa_user_sgpr_kernarg_segment_ptr 1
		.amdhsa_user_sgpr_dispatch_id 0
		.amdhsa_user_sgpr_kernarg_preload_length 0
		.amdhsa_user_sgpr_kernarg_preload_offset 0
		.amdhsa_user_sgpr_private_segment_size 0
		.amdhsa_uses_dynamic_stack 0
		.amdhsa_enable_private_segment 0
		.amdhsa_system_sgpr_workgroup_id_x 1
		.amdhsa_system_sgpr_workgroup_id_y 0
		.amdhsa_system_sgpr_workgroup_id_z 0
		.amdhsa_system_sgpr_workgroup_info 0
		.amdhsa_system_vgpr_workitem_id 2
		.amdhsa_next_free_vgpr 256
		.amdhsa_next_free_sgpr 102
		.amdhsa_accum_offset 256
		.amdhsa_reserve_vcc 1
		.amdhsa_float_round_mode_32 0
		.amdhsa_float_round_mode_16_64 0
		.amdhsa_float_denorm_mode_32 3
		.amdhsa_float_denorm_mode_16_64 3
		.amdhsa_dx10_clamp 1
		.amdhsa_ieee_mode 1
		.amdhsa_fp16_overflow 0
		.amdhsa_tg_split 0
		.amdhsa_exception_fp_ieee_invalid_op 0
		.amdhsa_exception_fp_denorm_src 0
		.amdhsa_exception_fp_ieee_div_zero 0
		.amdhsa_exception_fp_ieee_overflow 0
		.amdhsa_exception_fp_ieee_underflow 0
		.amdhsa_exception_fp_ieee_inexact 0
		.amdhsa_exception_int_div_zero 0
	.end_amdhsa_kernel

; __global__ void __launch_bounds__(256, 2) mega(Params p, int ph_lo, int ph_hi) {
;   __shared__ __attribute__((aligned(16))) char smem[SMEM_BYTES];
amdhsa.kernels:
  - .agpr_count:     0
    .args:
      - .offset:         0
        .size:           256
        .value_kind:     by_value
      - .offset:         256
        .size:           4
        .value_kind:     by_value
      - .offset:         260
        .size:           4
        .value_kind:     by_value
      - .offset:         264
        .size:           4
        .value_kind:     hidden_block_count_x
      - .offset:         268
        .size:           4
        .value_kind:     hidden_block_count_y
      - .offset:         272
        .size:           4
        .value_kind:     hidden_block_count_z
      - .offset:         276
        .size:           2
        .value_kind:     hidden_group_size_x
      - .offset:         278
        .size:           2
        .value_kind:     hidden_group_size_y
      - .offset:         280
        .size:           2
        .value_kind:     hidden_group_size_z
      - .offset:         282
        .size:           2
        .value_kind:     hidden_remainder_x
      - .offset:         284
        .size:           2
        .value_kind:     hidden_remainder_y
      - .offset:         286
        .size:           2
        .value_kind:     hidden_remainder_z
      - .offset:         304
        .size:           8
        .value_kind:     hidden_global_offset_x
      - .offset:         312
        .size:           8
        .value_kind:     hidden_global_offset_y
      - .offset:         320
        .size:           8
        .value_kind:     hidden_global_offset_z
      - .offset:         328
        .size:           2
        .value_kind:     hidden_grid_dims
      - .offset:         352
        .size:           8
        .value_kind:     hidden_multigrid_sync_arg
    .group_segment_fixed_size: 49180
    .kernarg_segment_align: 8
    .kernarg_segment_size: 520
    .language:       OpenCL C
    .language_version:
      - 2
      - 0
    .max_flat_workgroup_size: 256
    .name:           _Z4mega6Paramsii
    .private_segment_fixed_size: 0
    .sgpr_count:     108
    .sgpr_spill_count: 258
    .symbol:         _Z4mega6Paramsii.kd
    .uniform_work_group_size: 1
    .uses_dynamic_stack: false
    .vgpr_count:     256
    .vgpr_spill_count: 0
    .wavefront_size: 64
